# GEMM K-loops: LDS staging writes + prefetch loads moved from in front of the last MFMA block to the first MFMA block of each K-step (write after the barrier); same numerics
# speedup vs baseline: 1.0532x; 1.0152x over previous
.LBB0_208:
	s_add_i32 s12, s37, -2
	s_and_b32 s12, s12, 2
	s_mul_i32 s12, s12, 0x9000
	s_add_i32 s12, s12, 0
	v_add3_u32 v200, s12, v195, v192
	ds_read_b128 v[160:163], v200
	ds_read_b128 v[168:171], v200 offset:4608
	ds_read_b128 v[172:175], v200 offset:9216
	ds_read_b128 v[176:179], v200 offset:13824
	v_add3_u32 v214, s12, v194, v192
	ds_read_b128 v[164:167], v214 offset:36864
	s_cmpk_eq_i32 s2, 0x780
	s_waitcnt lgkmcnt(0)
	v_mfma_f32_32x32x16_bf16 v[112:127], v[160:163], v[164:167], v[112:127]
	v_mfma_f32_32x32x16_bf16 v[80:95], v[168:171], v[164:167], v[80:95]
	v_mfma_f32_32x32x16_bf16 v[48:63], v[172:175], v[164:167], v[48:63]
	v_mfma_f32_32x32x16_bf16 v[16:31], v[176:179], v[164:167], v[16:31]
	ds_read_b128 v[164:167], v214 offset:41472
	s_waitcnt lgkmcnt(0)
	v_mfma_f32_32x32x16_bf16 v[96:111], v[160:163], v[164:167], v[96:111]
	v_mfma_f32_32x32x16_bf16 v[64:79], v[168:171], v[164:167], v[64:79]
	v_mfma_f32_32x32x16_bf16 v[32:47], v[172:175], v[164:167], v[32:47]
	s_cbranch_scc1 .Lstg_done_0
	s_and_b32 s12, s37, 2
	s_mul_i32 s12, s12, 0x9000
	v_add_u32_e32 v215, s12, v193
	s_cmp_gt_u32 s34, 13
	s_waitcnt vmcnt(7)
	ds_write_b128 v215, v[128:131]
	s_waitcnt vmcnt(6)
	ds_write_b128 v215, v[132:135] offset:36864
	s_waitcnt vmcnt(5)
	ds_write_b128 v215, v[136:139] offset:9216
	s_waitcnt vmcnt(4)
	ds_write_b128 v215, v[140:143] offset:46080
	s_waitcnt vmcnt(3)
	ds_write_b128 v215, v[144:147] offset:18432
	s_waitcnt vmcnt(2)
	ds_write_b128 v215, v[148:151] offset:55296
	s_waitcnt vmcnt(1)
	ds_write_b128 v215, v[152:155] offset:27648
	s_waitcnt vmcnt(0)
	ds_write_b128 v215, v[156:159] offset:64512
	s_cbranch_scc1 .Lstg_done_0
	s_add_u32 s96, s92, s2
	s_addc_u32 s97, s93, s3
	s_add_u32 s98, s94, s2
	s_addc_u32 s99, s95, s3
	global_load_dwordx4 v[128:131], v248, s[96:97] offset:256
	global_load_dwordx4 v[132:135], v248, s[98:99] offset:256
	global_load_dwordx4 v[136:139], v249, s[96:97] offset:256
	global_load_dwordx4 v[140:143], v249, s[98:99] offset:256
	global_load_dwordx4 v[144:147], v250, s[96:97] offset:256
	global_load_dwordx4 v[148:151], v250, s[98:99] offset:256
	global_load_dwordx4 v[152:155], v251, s[96:97] offset:256
	global_load_dwordx4 v[156:159], v251, s[98:99] offset:256
.Lstg_done_0:
	ds_read_b128 v[160:163], v214 offset:36896
	ds_read_b128 v[168:171], v200 offset:32
	ds_read_b128 v[172:175], v200 offset:4640
	ds_read_b128 v[180:183], v200 offset:9248
	ds_read_b128 v[196:199], v200 offset:13856
	ds_read_b128 v[202:205], v214 offset:41504
	v_mfma_f32_32x32x16_bf16 v[0:15], v[176:179], v[164:167], v[0:15]
	s_waitcnt lgkmcnt(4)
	v_mfma_f32_32x32x16_bf16 v[112:127], v[168:171], v[160:163], v[112:127]
	s_waitcnt lgkmcnt(3)
	v_mfma_f32_32x32x16_bf16 v[80:95], v[172:175], v[160:163], v[80:95]
	s_waitcnt lgkmcnt(2)
	v_mfma_f32_32x32x16_bf16 v[48:63], v[180:183], v[160:163], v[48:63]
	s_waitcnt lgkmcnt(1)
	v_mfma_f32_32x32x16_bf16 v[16:31], v[196:199], v[160:163], v[16:31]
	s_waitcnt lgkmcnt(0)
	v_mfma_f32_32x32x16_bf16 v[96:111], v[168:171], v[202:205], v[96:111]
	v_mfma_f32_32x32x16_bf16 v[64:79], v[172:175], v[202:205], v[64:79]
	ds_read_b128 v[160:163], v214 offset:36928
	ds_read_b128 v[206:209], v214 offset:41536
	ds_read_b128 v[164:167], v200 offset:64
	ds_read_b128 v[168:171], v200 offset:4672
	ds_read_b128 v[172:175], v200 offset:9280
	ds_read_b128 v[210:213], v200 offset:13888
	v_mfma_f32_32x32x16_bf16 v[32:47], v[180:183], v[202:205], v[32:47]
	v_mfma_f32_32x32x16_bf16 v[0:15], v[196:199], v[202:205], v[0:15]
	s_waitcnt lgkmcnt(3)
	v_mfma_f32_32x32x16_bf16 v[112:127], v[164:167], v[160:163], v[112:127]
	s_waitcnt lgkmcnt(2)
	v_mfma_f32_32x32x16_bf16 v[80:95], v[168:171], v[160:163], v[80:95]
	s_waitcnt lgkmcnt(1)
	v_mfma_f32_32x32x16_bf16 v[48:63], v[172:175], v[160:163], v[48:63]
	s_waitcnt lgkmcnt(0)
	v_mfma_f32_32x32x16_bf16 v[16:31], v[210:213], v[160:163], v[16:31]
	v_mfma_f32_32x32x16_bf16 v[96:111], v[164:167], v[206:209], v[96:111]
	v_mfma_f32_32x32x16_bf16 v[64:79], v[168:171], v[206:209], v[64:79]
	v_mfma_f32_32x32x16_bf16 v[32:47], v[172:175], v[206:209], v[32:47]
	ds_read_b128 v[176:179], v214 offset:36960
	ds_read_b128 v[160:163], v214 offset:41568
	ds_read_b128 v[180:183], v200 offset:96
	ds_read_b128 v[172:175], v200 offset:4704
	ds_read_b128 v[168:171], v200 offset:9312
	ds_read_b128 v[164:167], v200 offset:13920
	v_mfma_f32_32x32x16_bf16 v[0:15], v[210:213], v[206:209], v[0:15]
	s_branch .LBB0_207

.LBB0_216:
	s_add_i32 s12, s35, -2
	s_and_b32 s12, s12, 2
	s_mul_i32 s12, s12, 0x9000
	s_add_i32 s12, s12, 0
	v_add3_u32 v214, s12, v194, v192
	ds_read_b128 v[160:163], v214 offset:36864
	v_add3_u32 v215, s12, v195, v192
	ds_read_b128 v[164:167], v215
	ds_read_b128 v[168:171], v215 offset:4608
	ds_read_b128 v[172:175], v215 offset:9216
	ds_read_b128 v[176:179], v215 offset:13824
	s_cmpk_eq_i32 s2, 0x780
	s_waitcnt lgkmcnt(3)
	v_mfma_f32_32x32x16_bf16 v[112:127], v[160:163], v[164:167], v[112:127]
	s_waitcnt lgkmcnt(2)
	v_mfma_f32_32x32x16_bf16 v[80:95], v[160:163], v[168:171], v[80:95]
	s_waitcnt lgkmcnt(1)
	v_mfma_f32_32x32x16_bf16 v[48:63], v[160:163], v[172:175], v[48:63]
	s_waitcnt lgkmcnt(0)
	v_mfma_f32_32x32x16_bf16 v[16:31], v[160:163], v[176:179], v[16:31]
	ds_read_b128 v[160:163], v214 offset:41472
	s_waitcnt lgkmcnt(0)
	v_mfma_f32_32x32x16_bf16 v[96:111], v[160:163], v[164:167], v[96:111]
	v_mfma_f32_32x32x16_bf16 v[64:79], v[160:163], v[168:171], v[64:79]
	v_mfma_f32_32x32x16_bf16 v[32:47], v[160:163], v[172:175], v[32:47]
	s_cbranch_scc1 .Lstg_done_1
	s_and_b32 s12, s35, 2
	s_mul_i32 s12, s12, 0x9000
	v_add_u32_e32 v216, s12, v193
	s_cmp_gt_u32 s22, 13
	s_waitcnt vmcnt(7)
	ds_write_b128 v216, v[128:131]
	s_waitcnt vmcnt(6)
	ds_write_b128 v216, v[132:135] offset:36864
	s_waitcnt vmcnt(5)
	ds_write_b128 v216, v[136:139] offset:9216
	s_waitcnt vmcnt(4)
	ds_write_b128 v216, v[140:143] offset:46080
	s_waitcnt vmcnt(3)
	ds_write_b128 v216, v[144:147] offset:18432
	s_waitcnt vmcnt(2)
	ds_write_b128 v216, v[148:151] offset:55296
	s_waitcnt vmcnt(1)
	ds_write_b128 v216, v[152:155] offset:27648
	s_waitcnt vmcnt(0)
	ds_write_b128 v216, v[156:159] offset:64512
	s_cbranch_scc1 .Lstg_done_1
	s_add_u32 s96, s92, s2
	s_addc_u32 s97, s93, s3
	s_add_u32 s98, s94, s2
	s_addc_u32 s99, s95, s3
	global_load_dwordx4 v[128:131], v248, s[96:97] offset:256
	global_load_dwordx4 v[132:135], v248, s[98:99] offset:256
	global_load_dwordx4 v[136:139], v249, s[96:97] offset:256
	global_load_dwordx4 v[140:143], v249, s[98:99] offset:256
	global_load_dwordx4 v[144:147], v250, s[96:97] offset:256
	global_load_dwordx4 v[148:151], v250, s[98:99] offset:256
	global_load_dwordx4 v[152:155], v251, s[96:97] offset:256
	global_load_dwordx4 v[156:159], v251, s[98:99] offset:256
.Lstg_done_1:
	ds_read_b128 v[164:167], v214 offset:36896
	ds_read_b128 v[168:171], v215 offset:32
	ds_read_b128 v[172:175], v215 offset:4640
	ds_read_b128 v[180:183], v215 offset:9248
	ds_read_b128 v[196:199], v215 offset:13856
	ds_read_b128 v[202:205], v214 offset:41504
	v_mfma_f32_32x32x16_bf16 v[0:15], v[160:163], v[176:179], v[0:15]
	s_waitcnt lgkmcnt(4)
	v_mfma_f32_32x32x16_bf16 v[112:127], v[164:167], v[168:171], v[112:127]
	s_waitcnt lgkmcnt(3)
	v_mfma_f32_32x32x16_bf16 v[80:95], v[164:167], v[172:175], v[80:95]
	s_waitcnt lgkmcnt(2)
	v_mfma_f32_32x32x16_bf16 v[48:63], v[164:167], v[180:183], v[48:63]
	s_waitcnt lgkmcnt(1)
	v_mfma_f32_32x32x16_bf16 v[16:31], v[164:167], v[196:199], v[16:31]
	s_waitcnt lgkmcnt(0)
	v_mfma_f32_32x32x16_bf16 v[96:111], v[202:205], v[168:171], v[96:111]
	v_mfma_f32_32x32x16_bf16 v[64:79], v[202:205], v[172:175], v[64:79]
	ds_read_b128 v[160:163], v214 offset:36928
	ds_read_b128 v[206:209], v214 offset:41536
	ds_read_b128 v[164:167], v215 offset:64
	ds_read_b128 v[168:171], v215 offset:4672
	ds_read_b128 v[172:175], v215 offset:9280
	ds_read_b128 v[210:213], v215 offset:13888
	v_mfma_f32_32x32x16_bf16 v[32:47], v[202:205], v[180:183], v[32:47]
	v_mfma_f32_32x32x16_bf16 v[0:15], v[202:205], v[196:199], v[0:15]
	s_waitcnt lgkmcnt(3)
	v_mfma_f32_32x32x16_bf16 v[112:127], v[160:163], v[164:167], v[112:127]
	s_waitcnt lgkmcnt(2)
	v_mfma_f32_32x32x16_bf16 v[80:95], v[160:163], v[168:171], v[80:95]
	s_waitcnt lgkmcnt(1)
	v_mfma_f32_32x32x16_bf16 v[48:63], v[160:163], v[172:175], v[48:63]
	s_waitcnt lgkmcnt(0)
	v_mfma_f32_32x32x16_bf16 v[16:31], v[160:163], v[210:213], v[16:31]
	v_mfma_f32_32x32x16_bf16 v[96:111], v[206:209], v[164:167], v[96:111]
	v_mfma_f32_32x32x16_bf16 v[64:79], v[206:209], v[168:171], v[64:79]
	v_mfma_f32_32x32x16_bf16 v[32:47], v[206:209], v[172:175], v[32:47]
	ds_read_b128 v[176:179], v214 offset:36960
	ds_read_b128 v[160:163], v214 offset:41568
	ds_read_b128 v[180:183], v215 offset:96
	ds_read_b128 v[172:175], v215 offset:4704
	ds_read_b128 v[168:171], v215 offset:9312
	ds_read_b128 v[164:167], v215 offset:13920
	v_mfma_f32_32x32x16_bf16 v[0:15], v[206:209], v[210:213], v[0:15]
	s_branch .LBB0_215

.LBB0_448:
	s_add_i32 s12, s36, -2
	s_and_b32 s12, s12, 2
	s_mul_i32 s12, s12, 0x9000
	s_add_i32 s12, s12, 0
	v_add3_u32 v193, s12, v192, v188
	ds_read_b128 v[160:163], v193
	ds_read_b128 v[168:171], v193 offset:4608
	ds_read_b128 v[172:175], v193 offset:9216
	ds_read_b128 v[176:179], v193 offset:13824
	v_add3_u32 v197, s12, v191, v188
	ds_read_b128 v[164:167], v197 offset:36864
	s_cmpk_eq_i32 s2, 0x780
	s_waitcnt lgkmcnt(0)
	v_mfma_f32_32x32x16_bf16 v[32:47], v[160:163], v[164:167], v[32:47]
	v_mfma_f32_32x32x16_bf16 v[64:79], v[168:171], v[164:167], v[64:79]
	v_mfma_f32_32x32x16_bf16 v[96:111], v[172:175], v[164:167], v[96:111]
	v_mfma_f32_32x32x16_bf16 v[112:127], v[176:179], v[164:167], v[112:127]
	ds_read_b128 v[164:167], v197 offset:41472
	s_waitcnt lgkmcnt(0)
	v_mfma_f32_32x32x16_bf16 v[0:15], v[160:163], v[164:167], v[0:15]
	v_mfma_f32_32x32x16_bf16 v[16:31], v[168:171], v[164:167], v[16:31]
	v_mfma_f32_32x32x16_bf16 v[48:63], v[172:175], v[164:167], v[48:63]
	s_cbranch_scc1 .Lstg_done_2
	s_and_b32 s12, s36, 2
	s_mul_i32 s12, s12, 0x9000
	v_add_u32_e32 v198, s12, v190
	s_cmp_gt_u32 s4, 13
	s_waitcnt vmcnt(7)
	ds_write_b128 v198, v[128:131]
	s_waitcnt vmcnt(6)
	ds_write_b128 v198, v[132:135] offset:36864
	s_waitcnt vmcnt(5)
	ds_write_b128 v198, v[136:139] offset:9216
	s_waitcnt vmcnt(4)
	ds_write_b128 v198, v[140:143] offset:46080
	s_waitcnt vmcnt(3)
	ds_write_b128 v198, v[144:147] offset:18432
	s_waitcnt vmcnt(2)
	ds_write_b128 v198, v[148:151] offset:55296
	s_waitcnt vmcnt(1)
	ds_write_b128 v198, v[152:155] offset:27648
	s_waitcnt vmcnt(0)
	ds_write_b128 v198, v[156:159] offset:64512
	s_cbranch_scc1 .Lstg_done_2
	s_add_u32 s96, s92, s2
	s_addc_u32 s97, s93, s3
	s_add_u32 s98, s94, s2
	s_addc_u32 s99, s95, s3
	global_load_dwordx4 v[128:131], v248, s[96:97] offset:256
	global_load_dwordx4 v[132:135], v248, s[98:99] offset:256
	global_load_dwordx4 v[136:139], v249, s[96:97] offset:256
	global_load_dwordx4 v[140:143], v249, s[98:99] offset:256
	global_load_dwordx4 v[144:147], v250, s[96:97] offset:256
	global_load_dwordx4 v[148:151], v250, s[98:99] offset:256
	global_load_dwordx4 v[152:155], v251, s[96:97] offset:256
	global_load_dwordx4 v[156:159], v251, s[98:99] offset:256
.Lstg_done_2:
	ds_read_b128 v[160:163], v197 offset:36896
	ds_read_b128 v[168:171], v193 offset:32
	ds_read_b128 v[172:175], v193 offset:4640
	ds_read_b128 v[180:183], v193 offset:9248
	ds_read_b128 v[202:205], v193 offset:13856
	ds_read_b128 v[206:209], v197 offset:41504
	v_mfma_f32_32x32x16_bf16 v[80:95], v[176:179], v[164:167], v[80:95]
	s_waitcnt lgkmcnt(4)
	v_mfma_f32_32x32x16_bf16 v[32:47], v[168:171], v[160:163], v[32:47]
	s_waitcnt lgkmcnt(3)
	v_mfma_f32_32x32x16_bf16 v[64:79], v[172:175], v[160:163], v[64:79]
	s_waitcnt lgkmcnt(2)
	v_mfma_f32_32x32x16_bf16 v[96:111], v[180:183], v[160:163], v[96:111]
	s_waitcnt lgkmcnt(1)
	v_mfma_f32_32x32x16_bf16 v[112:127], v[202:205], v[160:163], v[112:127]
	s_waitcnt lgkmcnt(0)
	v_mfma_f32_32x32x16_bf16 v[0:15], v[168:171], v[206:209], v[0:15]
	v_mfma_f32_32x32x16_bf16 v[16:31], v[172:175], v[206:209], v[16:31]
	ds_read_b128 v[160:163], v197 offset:36928
	ds_read_b128 v[210:213], v197 offset:41536
	ds_read_b128 v[164:167], v193 offset:64
	ds_read_b128 v[168:171], v193 offset:4672
	ds_read_b128 v[172:175], v193 offset:9280
	ds_read_b128 v[214:217], v193 offset:13888
	v_mfma_f32_32x32x16_bf16 v[48:63], v[180:183], v[206:209], v[48:63]
	v_mfma_f32_32x32x16_bf16 v[80:95], v[202:205], v[206:209], v[80:95]
	s_waitcnt lgkmcnt(3)
	v_mfma_f32_32x32x16_bf16 v[32:47], v[164:167], v[160:163], v[32:47]
	s_waitcnt lgkmcnt(2)
	v_mfma_f32_32x32x16_bf16 v[64:79], v[168:171], v[160:163], v[64:79]
	s_waitcnt lgkmcnt(1)
	v_mfma_f32_32x32x16_bf16 v[96:111], v[172:175], v[160:163], v[96:111]
	s_waitcnt lgkmcnt(0)
	v_mfma_f32_32x32x16_bf16 v[112:127], v[214:217], v[160:163], v[112:127]
	v_mfma_f32_32x32x16_bf16 v[0:15], v[164:167], v[210:213], v[0:15]
	v_mfma_f32_32x32x16_bf16 v[16:31], v[168:171], v[210:213], v[16:31]
	v_mfma_f32_32x32x16_bf16 v[48:63], v[172:175], v[210:213], v[48:63]
	ds_read_b128 v[176:179], v197 offset:36960
	ds_read_b128 v[160:163], v197 offset:41568
	ds_read_b128 v[180:183], v193 offset:96
	ds_read_b128 v[172:175], v193 offset:4704
	ds_read_b128 v[168:171], v193 offset:9312
	ds_read_b128 v[164:167], v193 offset:13920
	v_mfma_f32_32x32x16_bf16 v[80:95], v[214:217], v[210:213], v[80:95]
	s_branch .LBB0_447

.LBB0_460:
	s_add_i32 s12, s5, -2
	s_and_b32 s12, s12, 2
	s_mul_i32 s12, s12, 0x9000
	s_add_i32 s12, s12, 0
	v_add3_u32 v195, s12, v192, v194
	ds_read_b128 v[160:163], v195 offset:36864
	v_add3_u32 v200, s12, v193, v194
	ds_read_b128 v[164:167], v200
	ds_read_b128 v[168:171], v200 offset:4608
	ds_read_b128 v[172:175], v200 offset:9216
	ds_read_b128 v[176:179], v200 offset:13824
	s_cmpk_eq_i32 s2, 0x780
	s_waitcnt lgkmcnt(3)
	v_mfma_f32_32x32x16_bf16 v[112:127], v[160:163], v[164:167], v[112:127]
	s_waitcnt lgkmcnt(2)
	v_mfma_f32_32x32x16_bf16 v[96:111], v[160:163], v[168:171], v[96:111]
	s_waitcnt lgkmcnt(1)
	v_mfma_f32_32x32x16_bf16 v[80:95], v[160:163], v[172:175], v[80:95]
	s_waitcnt lgkmcnt(0)
	v_mfma_f32_32x32x16_bf16 v[48:63], v[160:163], v[176:179], v[48:63]
	ds_read_b128 v[160:163], v195 offset:41472
	s_waitcnt lgkmcnt(0)
	v_mfma_f32_32x32x16_bf16 v[64:79], v[160:163], v[164:167], v[64:79]
	v_mfma_f32_32x32x16_bf16 v[32:47], v[160:163], v[168:171], v[32:47]
	v_mfma_f32_32x32x16_bf16 v[16:31], v[160:163], v[172:175], v[16:31]
	s_cbranch_scc1 .Lstg_done_3
	s_and_b32 s12, s5, 2
	s_mul_i32 s12, s12, 0x9000
	v_add_u32_e32 v206, s12, v185
	s_cmp_gt_u32 s4, 13
	s_waitcnt vmcnt(7)
	ds_write_b128 v206, v[128:131]
	s_waitcnt vmcnt(6)
	ds_write_b128 v206, v[132:135] offset:36864
	s_waitcnt vmcnt(5)
	ds_write_b128 v206, v[136:139] offset:9216
	s_waitcnt vmcnt(4)
	ds_write_b128 v206, v[140:143] offset:46080
	s_waitcnt vmcnt(3)
	ds_write_b128 v206, v[144:147] offset:18432
	s_waitcnt vmcnt(2)
	ds_write_b128 v206, v[148:151] offset:55296
	s_waitcnt vmcnt(1)
	ds_write_b128 v206, v[152:155] offset:27648
	s_waitcnt vmcnt(0)
	ds_write_b128 v206, v[156:159] offset:64512
	s_cbranch_scc1 .Lstg_done_3
	s_add_u32 s96, s92, s2
	s_addc_u32 s97, s93, s3
	s_add_u32 s98, s94, s2
	s_addc_u32 s99, s95, s3
	global_load_dwordx4 v[128:131], v248, s[96:97] offset:256
	global_load_dwordx4 v[132:135], v248, s[98:99] offset:256
	global_load_dwordx4 v[136:139], v249, s[96:97] offset:256
	global_load_dwordx4 v[140:143], v249, s[98:99] offset:256
	global_load_dwordx4 v[144:147], v250, s[96:97] offset:256
	global_load_dwordx4 v[148:151], v250, s[98:99] offset:256
	global_load_dwordx4 v[152:155], v251, s[96:97] offset:256
	global_load_dwordx4 v[156:159], v251, s[98:99] offset:256
.Lstg_done_3:
	ds_read_b128 v[164:167], v195 offset:36896
	ds_read_b128 v[168:171], v200 offset:32
	ds_read_b128 v[172:175], v200 offset:4640
	ds_read_b128 v[180:183], v200 offset:9248
	ds_read_b128 v[196:199], v200 offset:13856
	ds_read_b128 v[202:205], v195 offset:41504
	v_mfma_f32_32x32x16_bf16 v[0:15], v[160:163], v[176:179], v[0:15]
	s_waitcnt lgkmcnt(4)
	v_mfma_f32_32x32x16_bf16 v[112:127], v[164:167], v[168:171], v[112:127]
	s_waitcnt lgkmcnt(3)
	v_mfma_f32_32x32x16_bf16 v[96:111], v[164:167], v[172:175], v[96:111]
	s_waitcnt lgkmcnt(2)
	v_mfma_f32_32x32x16_bf16 v[80:95], v[164:167], v[180:183], v[80:95]
	s_waitcnt lgkmcnt(1)
	v_mfma_f32_32x32x16_bf16 v[48:63], v[164:167], v[196:199], v[48:63]
	s_waitcnt lgkmcnt(0)
	v_mfma_f32_32x32x16_bf16 v[64:79], v[202:205], v[168:171], v[64:79]
	v_mfma_f32_32x32x16_bf16 v[32:47], v[202:205], v[172:175], v[32:47]
	ds_read_b128 v[160:163], v195 offset:36928
	ds_read_b128 v[210:213], v195 offset:41536
	ds_read_b128 v[164:167], v200 offset:64
	ds_read_b128 v[168:171], v200 offset:4672
	ds_read_b128 v[172:175], v200 offset:9280
	ds_read_b128 v[216:219], v200 offset:13888
	v_mfma_f32_32x32x16_bf16 v[16:31], v[202:205], v[180:183], v[16:31]
	v_mfma_f32_32x32x16_bf16 v[0:15], v[202:205], v[196:199], v[0:15]
	s_waitcnt lgkmcnt(3)
	v_mfma_f32_32x32x16_bf16 v[112:127], v[160:163], v[164:167], v[112:127]
	s_waitcnt lgkmcnt(2)
	v_mfma_f32_32x32x16_bf16 v[96:111], v[160:163], v[168:171], v[96:111]
	s_waitcnt lgkmcnt(1)
	v_mfma_f32_32x32x16_bf16 v[80:95], v[160:163], v[172:175], v[80:95]
	s_waitcnt lgkmcnt(0)
	v_mfma_f32_32x32x16_bf16 v[48:63], v[160:163], v[216:219], v[48:63]
	v_mfma_f32_32x32x16_bf16 v[64:79], v[210:213], v[164:167], v[64:79]
	v_mfma_f32_32x32x16_bf16 v[32:47], v[210:213], v[168:171], v[32:47]
	v_mfma_f32_32x32x16_bf16 v[16:31], v[210:213], v[172:175], v[16:31]
	ds_read_b128 v[176:179], v195 offset:36960
	ds_read_b128 v[160:163], v195 offset:41568
	ds_read_b128 v[180:183], v200 offset:96
	ds_read_b128 v[172:175], v200 offset:4704
	ds_read_b128 v[168:171], v200 offset:9312
	ds_read_b128 v[164:167], v200 offset:13920
	v_mfma_f32_32x32x16_bf16 v[0:15], v[210:213], v[216:219], v[0:15]
	s_branch .LBB0_459

.LBB0_640:
	s_and_b32 s12, s38, 2
	s_mul_i32 s12, s12, 0x9000
	s_add_i32 s12, s12, 0
	v_add3_u32 v197, s12, v196, v195
	ds_read_b128 v[160:163], v197 offset:36864
	v_add3_u32 v198, s12, v194, v195
	ds_read_b128 v[164:167], v198
	ds_read_b128 v[168:171], v198 offset:4608
	ds_read_b128 v[172:175], v198 offset:9216
	ds_read_b128 v[176:179], v198 offset:13824
	s_cmp_lt_u32 s41, 15
	s_waitcnt lgkmcnt(3)
	v_mfma_f32_32x32x16_bf16 v[112:127], v[160:163], v[164:167], v[112:127]
	s_waitcnt lgkmcnt(2)
	v_mfma_f32_32x32x16_bf16 v[80:95], v[160:163], v[168:171], v[80:95]
	s_waitcnt lgkmcnt(1)
	v_mfma_f32_32x32x16_bf16 v[48:63], v[160:163], v[172:175], v[48:63]
	s_waitcnt lgkmcnt(0)
	v_mfma_f32_32x32x16_bf16 v[16:31], v[160:163], v[176:179], v[16:31]
	ds_read_b128 v[160:163], v197 offset:41472
	s_waitcnt lgkmcnt(0)
	v_mfma_f32_32x32x16_bf16 v[96:111], v[160:163], v[164:167], v[96:111]
	v_mfma_f32_32x32x16_bf16 v[64:79], v[160:163], v[168:171], v[64:79]
	v_mfma_f32_32x32x16_bf16 v[32:47], v[160:163], v[172:175], v[32:47]
	s_cbranch_scc0 .Lstgb_skip_0
	s_add_i32 s38, s38, 2
	s_and_b32 s12, s38, 2
	s_mul_i32 s12, s12, 0x9000
	v_add_u32_e32 v199, s12, v193
	s_cmpk_eq_i32 s2, 0x700
	s_waitcnt vmcnt(0)
	ds_write_b128 v199, v[128:131]
	ds_write_b128 v199, v[132:135] offset:36864
	ds_write_b128 v199, v[136:139] offset:9216
	ds_write_b128 v199, v[140:143] offset:46080
	ds_write_b128 v199, v[144:147] offset:18432
	ds_write_b128 v199, v[148:151] offset:55296
	ds_write_b128 v199, v[152:155] offset:27648
	ds_write_b128 v199, v[156:159] offset:64512
	s_cbranch_scc1 .Lstgb_done_0
	s_add_u32 s96, s92, s2
	s_addc_u32 s97, s93, s3
	s_add_u32 s98, s94, s2
	s_addc_u32 s99, s95, s3
	global_load_dwordx4 v[128:131], v248, s[96:97] offset:256
	global_load_dwordx4 v[132:135], v248, s[98:99] offset:256
	global_load_dwordx4 v[136:139], v249, s[96:97] offset:256
	global_load_dwordx4 v[140:143], v249, s[98:99] offset:256
	global_load_dwordx4 v[144:147], v250, s[96:97] offset:256
	global_load_dwordx4 v[148:151], v250, s[98:99] offset:256
	global_load_dwordx4 v[152:155], v251, s[96:97] offset:256
	global_load_dwordx4 v[156:159], v251, s[98:99] offset:256
	s_branch .Lstgb_done_0
.Lstgb_skip_0:
	s_add_i32 s38, s38, 2
.Lstgb_done_0:
	ds_read_b128 v[164:167], v197 offset:36896
	ds_read_b128 v[168:171], v198 offset:32
	ds_read_b128 v[172:175], v198 offset:4640
	ds_read_b128 v[180:183], v198 offset:9248
	ds_read_b128 v[202:205], v198 offset:13856
	ds_read_b128 v[206:209], v197 offset:41504
	v_mfma_f32_32x32x16_bf16 v[0:15], v[160:163], v[176:179], v[0:15]
	s_waitcnt lgkmcnt(4)
	v_mfma_f32_32x32x16_bf16 v[112:127], v[164:167], v[168:171], v[112:127]
	s_waitcnt lgkmcnt(3)
	v_mfma_f32_32x32x16_bf16 v[80:95], v[164:167], v[172:175], v[80:95]
	s_waitcnt lgkmcnt(2)
	v_mfma_f32_32x32x16_bf16 v[48:63], v[164:167], v[180:183], v[48:63]
	s_waitcnt lgkmcnt(1)
	v_mfma_f32_32x32x16_bf16 v[16:31], v[164:167], v[202:205], v[16:31]
	s_waitcnt lgkmcnt(0)
	v_mfma_f32_32x32x16_bf16 v[96:111], v[206:209], v[168:171], v[96:111]
	v_mfma_f32_32x32x16_bf16 v[64:79], v[206:209], v[172:175], v[64:79]
	ds_read_b128 v[160:163], v197 offset:36928
	ds_read_b128 v[210:213], v197 offset:41536
	ds_read_b128 v[164:167], v198 offset:64
	ds_read_b128 v[168:171], v198 offset:4672
	ds_read_b128 v[172:175], v198 offset:9280
	ds_read_b128 v[214:217], v198 offset:13888
	v_mfma_f32_32x32x16_bf16 v[32:47], v[206:209], v[180:183], v[32:47]
	v_mfma_f32_32x32x16_bf16 v[0:15], v[206:209], v[202:205], v[0:15]
	s_waitcnt lgkmcnt(3)
	v_mfma_f32_32x32x16_bf16 v[112:127], v[160:163], v[164:167], v[112:127]
	s_waitcnt lgkmcnt(2)
	v_mfma_f32_32x32x16_bf16 v[80:95], v[160:163], v[168:171], v[80:95]
	s_waitcnt lgkmcnt(1)
	v_mfma_f32_32x32x16_bf16 v[48:63], v[160:163], v[172:175], v[48:63]
	s_waitcnt lgkmcnt(0)
	v_mfma_f32_32x32x16_bf16 v[16:31], v[160:163], v[214:217], v[16:31]
	v_mfma_f32_32x32x16_bf16 v[96:111], v[210:213], v[164:167], v[96:111]
	v_mfma_f32_32x32x16_bf16 v[64:79], v[210:213], v[168:171], v[64:79]
	v_mfma_f32_32x32x16_bf16 v[32:47], v[210:213], v[172:175], v[32:47]
	ds_read_b128 v[176:179], v197 offset:36960
	ds_read_b128 v[160:163], v197 offset:41568
	ds_read_b128 v[180:183], v198 offset:96
	ds_read_b128 v[172:175], v198 offset:4704
	ds_read_b128 v[168:171], v198 offset:9312
	ds_read_b128 v[164:167], v198 offset:13920
	v_mfma_f32_32x32x16_bf16 v[0:15], v[210:213], v[214:217], v[0:15]
	s_branch .LBB0_639

.LBB0_758:
	s_add_i32 s12, s16, -2
	s_and_b32 s12, s12, 2
	s_mul_i32 s12, s12, 0x9000
	s_add_i32 s12, s12, 0
	v_add3_u32 v200, s12, v199, v198
	ds_read_b128 v[160:163], v200 offset:36864
	v_add3_u32 v218, s12, v185, v198
	ds_read_b128 v[164:167], v218
	ds_read_b128 v[168:171], v218 offset:4608
	ds_read_b128 v[172:175], v218 offset:9216
	ds_read_b128 v[176:179], v218 offset:13824
	s_cmpk_eq_i32 s4, 0x780
	s_waitcnt lgkmcnt(3)
	v_mfma_f32_32x32x16_bf16 v[112:127], v[160:163], v[164:167], v[112:127]
	s_waitcnt lgkmcnt(2)
	v_mfma_f32_32x32x16_bf16 v[96:111], v[160:163], v[168:171], v[96:111]
	s_waitcnt lgkmcnt(1)
	v_mfma_f32_32x32x16_bf16 v[80:95], v[160:163], v[172:175], v[80:95]
	s_waitcnt lgkmcnt(0)
	v_mfma_f32_32x32x16_bf16 v[48:63], v[160:163], v[176:179], v[48:63]
	ds_read_b128 v[160:163], v200 offset:41472
	s_waitcnt lgkmcnt(0)
	v_mfma_f32_32x32x16_bf16 v[64:79], v[160:163], v[164:167], v[64:79]
	v_mfma_f32_32x32x16_bf16 v[32:47], v[160:163], v[168:171], v[32:47]
	v_mfma_f32_32x32x16_bf16 v[16:31], v[160:163], v[172:175], v[16:31]
	s_cbranch_scc1 .Lstg_done_4
	s_and_b32 s12, s16, 2
	s_mul_i32 s12, s12, 0x9000
	s_add_i32 s12, s12, 0
	v_add_u32_e32 v220, s12, v194
	v_add_u32_e32 v219, s12, v184
	s_waitcnt vmcnt(7)
	ds_write_b128 v220, v[128:131]
	s_waitcnt vmcnt(6)
	ds_write_b128 v219, v[132:135] offset:36864
	v_add_u32_e32 v220, s12, v195
	s_waitcnt vmcnt(5)
	ds_write_b128 v220, v[136:139]
	s_waitcnt vmcnt(4)
	ds_write_b128 v219, v[140:143] offset:46080
	v_add_u32_e32 v220, s12, v196
	s_cmp_gt_u32 s35, 13
	s_waitcnt vmcnt(3)
	ds_write_b128 v220, v[144:147]
	s_waitcnt vmcnt(2)
	ds_write_b128 v219, v[148:151] offset:55296
	v_add_u32_e32 v220, s12, v197
	s_waitcnt vmcnt(1)
	ds_write_b128 v220, v[152:155]
	s_waitcnt vmcnt(0)
	ds_write_b128 v219, v[156:159] offset:64512
	s_cbranch_scc1 .Lstg_done_4
	s_add_u32 s96, s92, s4
	s_addc_u32 s97, s93, s5
	s_add_u32 s98, s94, s4
	s_addc_u32 s99, s95, s5
	global_load_dwordx4 v[128:131], v248, s[96:97] offset:256
	global_load_dwordx4 v[132:135], v248, s[98:99] offset:256
	global_load_dwordx4 v[136:139], v249, s[96:97] offset:256
	global_load_dwordx4 v[140:143], v249, s[98:99] offset:256
	global_load_dwordx4 v[144:147], v250, s[96:97] offset:256
	global_load_dwordx4 v[148:151], v250, s[98:99] offset:256
	global_load_dwordx4 v[152:155], v251, s[96:97] offset:256
	global_load_dwordx4 v[156:159], v251, s[98:99] offset:256
.Lstg_done_4:
	ds_read_b128 v[164:167], v200 offset:36896
	ds_read_b128 v[168:171], v218 offset:32
	ds_read_b128 v[172:175], v218 offset:4640
	ds_read_b128 v[180:183], v218 offset:9248
	ds_read_b128 v[202:205], v218 offset:13856
	ds_read_b128 v[206:209], v200 offset:41504
	v_mfma_f32_32x32x16_bf16 v[0:15], v[160:163], v[176:179], v[0:15]
	s_waitcnt lgkmcnt(4)
	v_mfma_f32_32x32x16_bf16 v[112:127], v[164:167], v[168:171], v[112:127]
	s_waitcnt lgkmcnt(3)
	v_mfma_f32_32x32x16_bf16 v[96:111], v[164:167], v[172:175], v[96:111]
	s_waitcnt lgkmcnt(2)
	v_mfma_f32_32x32x16_bf16 v[80:95], v[164:167], v[180:183], v[80:95]
	s_waitcnt lgkmcnt(1)
	v_mfma_f32_32x32x16_bf16 v[48:63], v[164:167], v[202:205], v[48:63]
	s_waitcnt lgkmcnt(0)
	v_mfma_f32_32x32x16_bf16 v[64:79], v[206:209], v[168:171], v[64:79]
	v_mfma_f32_32x32x16_bf16 v[32:47], v[206:209], v[172:175], v[32:47]
	ds_read_b128 v[160:163], v200 offset:36928
	ds_read_b128 v[210:213], v200 offset:41536
	ds_read_b128 v[164:167], v218 offset:64
	ds_read_b128 v[168:171], v218 offset:4672
	ds_read_b128 v[172:175], v218 offset:9280
	ds_read_b128 v[214:217], v218 offset:13888
	v_mfma_f32_32x32x16_bf16 v[16:31], v[206:209], v[180:183], v[16:31]
	v_mfma_f32_32x32x16_bf16 v[0:15], v[206:209], v[202:205], v[0:15]
	s_waitcnt lgkmcnt(3)
	v_mfma_f32_32x32x16_bf16 v[112:127], v[160:163], v[164:167], v[112:127]
	s_waitcnt lgkmcnt(2)
	v_mfma_f32_32x32x16_bf16 v[96:111], v[160:163], v[168:171], v[96:111]
	s_waitcnt lgkmcnt(1)
	v_mfma_f32_32x32x16_bf16 v[80:95], v[160:163], v[172:175], v[80:95]
	s_waitcnt lgkmcnt(0)
	v_mfma_f32_32x32x16_bf16 v[48:63], v[160:163], v[214:217], v[48:63]
	v_mfma_f32_32x32x16_bf16 v[64:79], v[210:213], v[164:167], v[64:79]
	v_mfma_f32_32x32x16_bf16 v[32:47], v[210:213], v[168:171], v[32:47]
	v_mfma_f32_32x32x16_bf16 v[16:31], v[210:213], v[172:175], v[16:31]
	ds_read_b128 v[176:179], v200 offset:36960
	ds_read_b128 v[160:163], v200 offset:41568
	ds_read_b128 v[180:183], v218 offset:96
	ds_read_b128 v[172:175], v218 offset:4704
	ds_read_b128 v[168:171], v218 offset:9312
	ds_read_b128 v[164:167], v218 offset:13920
	v_mfma_f32_32x32x16_bf16 v[0:15], v[210:213], v[214:217], v[0:15]
	s_branch .LBB0_757

.LBB0_799:
	s_add_i32 s12, s36, -2
	s_and_b32 s12, s12, 2
	s_mul_i32 s12, s12, 0x9000
	s_add_i32 s12, s12, 0
	v_add3_u32 v214, s12, v195, v194
	ds_read_b128 v[160:163], v214 offset:36864
	v_add3_u32 v215, s12, v193, v194
	ds_read_b128 v[164:167], v215
	ds_read_b128 v[168:171], v215 offset:4608
	ds_read_b128 v[172:175], v215 offset:9216
	ds_read_b128 v[176:179], v215 offset:13824
	s_cmpk_eq_i32 s4, 0x180
	s_waitcnt lgkmcnt(3)
	v_mfma_f32_32x32x16_bf16 v[112:127], v[160:163], v[164:167], v[112:127]
	s_waitcnt lgkmcnt(2)
	v_mfma_f32_32x32x16_bf16 v[96:111], v[160:163], v[168:171], v[96:111]
	s_waitcnt lgkmcnt(1)
	v_mfma_f32_32x32x16_bf16 v[64:79], v[160:163], v[172:175], v[64:79]
	s_waitcnt lgkmcnt(0)
	v_mfma_f32_32x32x16_bf16 v[32:47], v[160:163], v[176:179], v[32:47]
	ds_read_b128 v[160:163], v214 offset:41472
	s_waitcnt lgkmcnt(0)
	v_mfma_f32_32x32x16_bf16 v[80:95], v[160:163], v[164:167], v[80:95]
	v_mfma_f32_32x32x16_bf16 v[48:63], v[160:163], v[168:171], v[48:63]
	v_mfma_f32_32x32x16_bf16 v[16:31], v[160:163], v[172:175], v[16:31]
	s_cbranch_scc1 .Lstg_done_5
	s_and_b32 s12, s36, 2
	s_mul_i32 s12, s12, 0x9000
	v_add_u32_e32 v216, s12, v192
	s_cmp_gt_u32 s17, 1
	s_waitcnt vmcnt(7)
	ds_write_b128 v216, v[128:131]
	s_waitcnt vmcnt(6)
	ds_write_b128 v216, v[132:135] offset:36864
	s_waitcnt vmcnt(5)
	ds_write_b128 v216, v[136:139] offset:9216
	s_waitcnt vmcnt(4)
	ds_write_b128 v216, v[140:143] offset:46080
	s_waitcnt vmcnt(3)
	ds_write_b128 v216, v[144:147] offset:18432
	s_waitcnt vmcnt(2)
	ds_write_b128 v216, v[148:151] offset:55296
	s_waitcnt vmcnt(1)
	ds_write_b128 v216, v[152:155] offset:27648
	s_waitcnt vmcnt(0)
	ds_write_b128 v216, v[156:159] offset:64512
	s_cbranch_scc1 .Lstg_done_5
	s_add_u32 s96, s92, s4
	s_addc_u32 s97, s93, s5
	s_add_u32 s98, s94, s4
	s_addc_u32 s99, s95, s5
	global_load_dwordx4 v[128:131], v248, s[96:97] offset:256
	global_load_dwordx4 v[132:135], v248, s[98:99] offset:256
	global_load_dwordx4 v[136:139], v249, s[96:97] offset:256
	global_load_dwordx4 v[140:143], v249, s[98:99] offset:256
	global_load_dwordx4 v[144:147], v250, s[96:97] offset:256
	global_load_dwordx4 v[148:151], v250, s[98:99] offset:256
	global_load_dwordx4 v[152:155], v251, s[96:97] offset:256
	global_load_dwordx4 v[156:159], v251, s[98:99] offset:256
.Lstg_done_5:
	ds_read_b128 v[164:167], v214 offset:36896
	ds_read_b128 v[168:171], v215 offset:32
	ds_read_b128 v[172:175], v215 offset:4640
	ds_read_b128 v[180:183], v215 offset:9248
	ds_read_b128 v[196:199], v215 offset:13856
	ds_read_b128 v[202:205], v214 offset:41504
	v_mfma_f32_32x32x16_bf16 v[0:15], v[160:163], v[176:179], v[0:15]
	s_waitcnt lgkmcnt(4)
	v_mfma_f32_32x32x16_bf16 v[112:127], v[164:167], v[168:171], v[112:127]
	s_waitcnt lgkmcnt(3)
	v_mfma_f32_32x32x16_bf16 v[96:111], v[164:167], v[172:175], v[96:111]
	s_waitcnt lgkmcnt(2)
	v_mfma_f32_32x32x16_bf16 v[64:79], v[164:167], v[180:183], v[64:79]
	s_waitcnt lgkmcnt(1)
	v_mfma_f32_32x32x16_bf16 v[32:47], v[164:167], v[196:199], v[32:47]
	s_waitcnt lgkmcnt(0)
	v_mfma_f32_32x32x16_bf16 v[80:95], v[202:205], v[168:171], v[80:95]
	v_mfma_f32_32x32x16_bf16 v[48:63], v[202:205], v[172:175], v[48:63]
	ds_read_b128 v[160:163], v214 offset:36928
	ds_read_b128 v[206:209], v214 offset:41536
	ds_read_b128 v[164:167], v215 offset:64
	ds_read_b128 v[168:171], v215 offset:4672
	ds_read_b128 v[172:175], v215 offset:9280
	ds_read_b128 v[210:213], v215 offset:13888
	v_mfma_f32_32x32x16_bf16 v[16:31], v[202:205], v[180:183], v[16:31]
	v_mfma_f32_32x32x16_bf16 v[0:15], v[202:205], v[196:199], v[0:15]
	s_waitcnt lgkmcnt(3)
	v_mfma_f32_32x32x16_bf16 v[112:127], v[160:163], v[164:167], v[112:127]
	s_waitcnt lgkmcnt(2)
	v_mfma_f32_32x32x16_bf16 v[96:111], v[160:163], v[168:171], v[96:111]
	s_waitcnt lgkmcnt(1)
	v_mfma_f32_32x32x16_bf16 v[64:79], v[160:163], v[172:175], v[64:79]
	s_waitcnt lgkmcnt(0)
	v_mfma_f32_32x32x16_bf16 v[32:47], v[160:163], v[210:213], v[32:47]
	v_mfma_f32_32x32x16_bf16 v[80:95], v[206:209], v[164:167], v[80:95]
	v_mfma_f32_32x32x16_bf16 v[48:63], v[206:209], v[168:171], v[48:63]
	v_mfma_f32_32x32x16_bf16 v[16:31], v[206:209], v[172:175], v[16:31]
	ds_read_b128 v[176:179], v214 offset:36960
	ds_read_b128 v[160:163], v214 offset:41568
	ds_read_b128 v[180:183], v215 offset:96
	ds_read_b128 v[172:175], v215 offset:4704
	ds_read_b128 v[168:171], v215 offset:9312
	ds_read_b128 v[164:167], v215 offset:13920
	v_mfma_f32_32x32x16_bf16 v[0:15], v[206:209], v[210:213], v[0:15]
	s_branch .LBB0_798

.LBB0_958:
	s_and_b32 s6, s34, 2
	s_mul_i32 s6, s6, 0x9000
	s_add_i32 s6, s6, 0
	v_add3_u32 v214, s6, v195, v200
	ds_read_b128 v[160:163], v214 offset:36864
	v_add3_u32 v215, s6, v194, v200
	ds_read_b128 v[164:167], v215
	ds_read_b128 v[168:171], v215 offset:4608
	ds_read_b128 v[172:175], v215 offset:9216
	ds_read_b128 v[176:179], v215 offset:13824
	s_cmp_lt_u32 s39, 43
	s_waitcnt lgkmcnt(3)
	v_mfma_f32_32x32x16_bf16 v[112:127], v[160:163], v[164:167], v[112:127]
	s_waitcnt lgkmcnt(2)
	v_mfma_f32_32x32x16_bf16 v[80:95], v[160:163], v[168:171], v[80:95]
	s_waitcnt lgkmcnt(1)
	v_mfma_f32_32x32x16_bf16 v[48:63], v[160:163], v[172:175], v[48:63]
	s_waitcnt lgkmcnt(0)
	v_mfma_f32_32x32x16_bf16 v[16:31], v[160:163], v[176:179], v[16:31]
	ds_read_b128 v[160:163], v214 offset:41472
	s_waitcnt lgkmcnt(0)
	v_mfma_f32_32x32x16_bf16 v[96:111], v[160:163], v[164:167], v[96:111]
	v_mfma_f32_32x32x16_bf16 v[64:79], v[160:163], v[168:171], v[64:79]
	v_mfma_f32_32x32x16_bf16 v[32:47], v[160:163], v[172:175], v[32:47]
	s_cbranch_scc0 .Lstgb_skip_1
	s_add_i32 s34, s34, 2
	s_and_b32 s6, s34, 2
	s_mul_i32 s6, s6, 0x9000
	v_add_u32_e32 v216, s6, v193
	s_cmpk_eq_i32 s2, 0x1500
	s_waitcnt vmcnt(0)
	ds_write_b128 v216, v[128:131]
	ds_write_b128 v216, v[132:135] offset:36864
	ds_write_b128 v216, v[136:139] offset:9216
	ds_write_b128 v216, v[140:143] offset:46080
	ds_write_b128 v216, v[144:147] offset:18432
	ds_write_b128 v216, v[148:151] offset:55296
	ds_write_b128 v216, v[152:155] offset:27648
	ds_write_b128 v216, v[156:159] offset:64512
	s_cbranch_scc1 .Lstgb_done_1
	s_add_u32 s96, s92, s2
	s_addc_u32 s97, s93, s3
	s_add_u32 s98, s94, s2
	s_addc_u32 s99, s95, s3
	global_load_dwordx4 v[128:131], v248, s[96:97] offset:256
	global_load_dwordx4 v[132:135], v248, s[98:99] offset:256
	global_load_dwordx4 v[136:139], v249, s[96:97] offset:256
	global_load_dwordx4 v[140:143], v249, s[98:99] offset:256
	global_load_dwordx4 v[144:147], v250, s[96:97] offset:256
	global_load_dwordx4 v[148:151], v250, s[98:99] offset:256
	global_load_dwordx4 v[152:155], v251, s[96:97] offset:256
	global_load_dwordx4 v[156:159], v251, s[98:99] offset:256
	s_branch .Lstgb_done_1
.Lstgb_skip_1:
	s_add_i32 s34, s34, 2

.LBB0_1049:
	s_add_i32 s12, s35, -2
	s_and_b32 s12, s12, 2
	s_mul_i32 s12, s12, 0x9000
	s_add_i32 s12, s12, 0
	v_add3_u32 v200, s12, v195, v191
	ds_read_b128 v[160:163], v200 offset:36864
	v_add3_u32 v214, s12, v190, v191
	ds_read_b128 v[164:167], v214
	ds_read_b128 v[168:171], v214 offset:4608
	ds_read_b128 v[172:175], v214 offset:9216
	ds_read_b128 v[176:179], v214 offset:13824
	s_cmpk_eq_i32 s2, 0x780
	s_waitcnt lgkmcnt(3)
	v_mfma_f32_32x32x16_bf16 v[112:127], v[160:163], v[164:167], v[112:127]
	s_waitcnt lgkmcnt(2)
	v_mfma_f32_32x32x16_bf16 v[80:95], v[160:163], v[168:171], v[80:95]
	s_waitcnt lgkmcnt(1)
	v_mfma_f32_32x32x16_bf16 v[48:63], v[160:163], v[172:175], v[48:63]
	s_waitcnt lgkmcnt(0)
	v_mfma_f32_32x32x16_bf16 v[16:31], v[160:163], v[176:179], v[16:31]
	ds_read_b128 v[160:163], v200 offset:41472
	s_waitcnt lgkmcnt(0)
	v_mfma_f32_32x32x16_bf16 v[96:111], v[160:163], v[164:167], v[96:111]
	v_mfma_f32_32x32x16_bf16 v[64:79], v[160:163], v[168:171], v[64:79]
	v_mfma_f32_32x32x16_bf16 v[32:47], v[160:163], v[172:175], v[32:47]
	s_cbranch_scc1 .Lstg_done_6
	s_and_b32 s12, s35, 2
	s_mul_i32 s12, s12, 0x9000
	v_add_u32_e32 v215, s12, v189
	s_cmp_gt_u32 s16, 13
	s_waitcnt vmcnt(7)
	ds_write_b128 v215, v[128:131]
	s_waitcnt vmcnt(6)
	ds_write_b128 v215, v[132:135] offset:36864
	s_waitcnt vmcnt(5)
	ds_write_b128 v215, v[136:139] offset:9216
	s_waitcnt vmcnt(4)
	ds_write_b128 v215, v[140:143] offset:46080
	s_waitcnt vmcnt(3)
	ds_write_b128 v215, v[144:147] offset:18432
	s_waitcnt vmcnt(2)
	ds_write_b128 v215, v[148:151] offset:55296
	s_waitcnt vmcnt(1)
	ds_write_b128 v215, v[152:155] offset:27648
	s_waitcnt vmcnt(0)
	ds_write_b128 v215, v[156:159] offset:64512
	s_cbranch_scc1 .Lstg_done_6
	s_add_u32 s96, s92, s2
	s_addc_u32 s97, s93, s3
	s_add_u32 s98, s94, s2
	s_addc_u32 s99, s95, s3
	global_load_dwordx4 v[128:131], v248, s[96:97] offset:256
	global_load_dwordx4 v[132:135], v248, s[98:99] offset:256
	global_load_dwordx4 v[136:139], v249, s[96:97] offset:256
	global_load_dwordx4 v[140:143], v249, s[98:99] offset:256
	global_load_dwordx4 v[144:147], v250, s[96:97] offset:256
	global_load_dwordx4 v[148:151], v250, s[98:99] offset:256
	global_load_dwordx4 v[152:155], v251, s[96:97] offset:256
	global_load_dwordx4 v[156:159], v251, s[98:99] offset:256
.Lstg_done_6:
	ds_read_b128 v[164:167], v200 offset:36896
	ds_read_b128 v[168:171], v214 offset:32
	ds_read_b128 v[172:175], v214 offset:4640
	ds_read_b128 v[180:183], v214 offset:9248
	ds_read_b128 v[196:199], v214 offset:13856
	ds_read_b128 v[202:205], v200 offset:41504
	v_mfma_f32_32x32x16_bf16 v[0:15], v[160:163], v[176:179], v[0:15]
	s_waitcnt lgkmcnt(4)
	v_mfma_f32_32x32x16_bf16 v[112:127], v[164:167], v[168:171], v[112:127]
	s_waitcnt lgkmcnt(3)
	v_mfma_f32_32x32x16_bf16 v[80:95], v[164:167], v[172:175], v[80:95]
	s_waitcnt lgkmcnt(2)
	v_mfma_f32_32x32x16_bf16 v[48:63], v[164:167], v[180:183], v[48:63]
	s_waitcnt lgkmcnt(1)
	v_mfma_f32_32x32x16_bf16 v[16:31], v[164:167], v[196:199], v[16:31]
	s_waitcnt lgkmcnt(0)
	v_mfma_f32_32x32x16_bf16 v[96:111], v[202:205], v[168:171], v[96:111]
	v_mfma_f32_32x32x16_bf16 v[64:79], v[202:205], v[172:175], v[64:79]
	ds_read_b128 v[160:163], v200 offset:36928
	ds_read_b128 v[206:209], v200 offset:41536
	ds_read_b128 v[164:167], v214 offset:64
	ds_read_b128 v[168:171], v214 offset:4672
	ds_read_b128 v[172:175], v214 offset:9280
	ds_read_b128 v[210:213], v214 offset:13888
	v_mfma_f32_32x32x16_bf16 v[32:47], v[202:205], v[180:183], v[32:47]
	v_mfma_f32_32x32x16_bf16 v[0:15], v[202:205], v[196:199], v[0:15]
	s_waitcnt lgkmcnt(3)
	v_mfma_f32_32x32x16_bf16 v[112:127], v[160:163], v[164:167], v[112:127]
	s_waitcnt lgkmcnt(2)
	v_mfma_f32_32x32x16_bf16 v[80:95], v[160:163], v[168:171], v[80:95]
	s_waitcnt lgkmcnt(1)
	v_mfma_f32_32x32x16_bf16 v[48:63], v[160:163], v[172:175], v[48:63]
	s_waitcnt lgkmcnt(0)
	v_mfma_f32_32x32x16_bf16 v[16:31], v[160:163], v[210:213], v[16:31]
	v_mfma_f32_32x32x16_bf16 v[96:111], v[206:209], v[164:167], v[96:111]
	v_mfma_f32_32x32x16_bf16 v[64:79], v[206:209], v[168:171], v[64:79]
	v_mfma_f32_32x32x16_bf16 v[32:47], v[206:209], v[172:175], v[32:47]
	ds_read_b128 v[176:179], v200 offset:36960
	ds_read_b128 v[160:163], v200 offset:41568
	ds_read_b128 v[180:183], v214 offset:96
	ds_read_b128 v[172:175], v214 offset:4704
	ds_read_b128 v[168:171], v214 offset:9312
	ds_read_b128 v[164:167], v214 offset:13920
	v_mfma_f32_32x32x16_bf16 v[0:15], v[206:209], v[210:213], v[0:15]
	s_branch .LBB0_1048
